# baseline (speedup 1.0000x reference)
; __device__ __forceinline__ int bidx() { int t = blockIdx.x; asm volatile("" : "+s"(t)); return t; }
; __device__ __forceinline__ void ln_phase(const h16* V, float* X, h16* Xh, const float* g, const float* b, bool final_out, bool dry = false) {
;     ...
;   for (int row = bidx() * 4 + wid; row < T_; row += gridDim.x * 4) {
;     const h16* vr = V + (size_t)row * 1024;
;     f4 v[4];
;     float s = 0.f;
; #pragma unroll
;     for (int i = 0; i < 4; ++i) {
;       h4 hv = *(const h4*)(vr + i * 256 + lane * 4);
;       v[i][0] = (float)hv[0]; v[i][1] = (float)hv[1]; v[i][2] = (float)hv[2]; v[i][3] = (float)hv[3];
;       s += v[i][0] + v[i][1] + v[i][2] + v[i][3];
;     }
;     for (int o = 32; o > 0; o >>= 1) s += __shfl_xor(s, o);
;     const float mu = s * (1.f / 1024.f);
;     float q = 0.f;
; #pragma unroll
;     for (int i = 0; i < 4; ++i)
; #pragma unroll
;       for (int j = 0; j < 4; ++j) { float d = v[i][j] - mu; q += d * d; }
;     for (int o = 32; o > 0; o >>= 1) q += __shfl_xor(q, o);
;     const float rs = rsqrtf(q * (1.f / 1024.f) + 1e-5f);
;     if (dry && rs != 12345.678f) continue;
; #pragma unroll
;     for (int i = 0; i < 4; ++i) {
;       int c = i * 256 + lane * 4;
;       f4 gg = *(const f4*)(g + c), bb = *(const f4*)(b + c), o;
;       h4 oh;
; #pragma unroll
;       for (int j = 0; j < 4; ++j) { o[j] = (v[i][j] - mu) * rs * gg[j] + bb[j]; oh[j] = (h16)o[j]; }
;       if (final_out) *(f4*)(X + (size_t)row * 1024 + c) = o;
;       else *(h4*)(Xh + (size_t)row * 1024 + c) = oh;
;     }
.LBB0_1193:
	v_ashrrev_i32_e32 v3, 31, v2
	v_lshlrev_b64 v[26:27], 11, v[2:3]
	v_lshl_add_u64 v[18:19], v[4:5], 0, v[26:27]
	global_load_dwordx2 v[20:21], v[18:19], off offset:1536
	global_load_dwordx2 v[22:23], v[18:19], off offset:1024
	global_load_dwordx2 v[24:25], v[18:19], off
	s_nop 0
	global_load_dwordx2 v[18:19], v[18:19], off offset:512
	v_add_u32_e32 v110, s77, v2
	v_ashrrev_i32_e32 v111, 31, v110
	v_lshlrev_b64 v[110:111], 11, v[110:111]
	v_lshl_add_u64 v[102:103], v[4:5], 0, v[110:111]
	global_load_dwordx2 v[104:105], v[102:103], off offset:1536
	global_load_dwordx2 v[106:107], v[102:103], off offset:1024
	global_load_dwordx2 v[108:109], v[102:103], off
	s_nop 0
	global_load_dwordx2 v[102:103], v[102:103], off offset:512
	v_mov_b32_e32 v28, v1
	v_lshl_add_u64 v[26:27], v[10:11], 0, v[26:27]
	v_add_u32_e32 v2, s77, v2
	s_waitcnt vmcnt(7)
	v_cvt_f32_f16_e32 v31, v20
	s_waitcnt vmcnt(6)
	v_cvt_f32_f16_e32 v30, v22
	s_waitcnt vmcnt(5)
	v_cvt_f32_f16_sdwa v39, v24 dst_sel:DWORD dst_unused:UNUSED_PAD src0_sel:WORD_1
	v_cvt_f32_f16_e32 v38, v24
	v_cvt_f32_f16_e32 v40, v25
	s_waitcnt vmcnt(4)
	v_cvt_f32_f16_e32 v42, v18
	v_cvt_f32_f16_sdwa v43, v18 dst_sel:DWORD dst_unused:UNUSED_PAD src0_sel:WORD_1
	v_cvt_f32_f16_sdwa v41, v25 dst_sel:DWORD dst_unused:UNUSED_PAD src0_sel:WORD_1
	v_cvt_f32_f16_e32 v44, v19
	v_cvt_f32_f16_sdwa v45, v19 dst_sel:DWORD dst_unused:UNUSED_PAD src0_sel:WORD_1
	v_cvt_f32_f16_sdwa v33, v20 dst_sel:DWORD dst_unused:UNUSED_PAD src0_sel:WORD_1
	v_cvt_f32_f16_sdwa v32, v22 dst_sel:DWORD dst_unused:UNUSED_PAD src0_sel:WORD_1
	v_mov_b32_e32 v0, v39
	v_cvt_f32_f16_e32 v35, v21
	v_cvt_f32_f16_e32 v34, v23
	v_pk_add_f32 v[24:25], v[0:1], v[38:39]
	v_cvt_f32_f16_sdwa v37, v21 dst_sel:DWORD dst_unused:UNUSED_PAD src0_sel:WORD_1
	v_cvt_f32_f16_sdwa v36, v23 dst_sel:DWORD dst_unused:UNUSED_PAD src0_sel:WORD_1
	v_mov_b32_e32 v20, v40
	v_mov_b32_e32 v21, v43
	v_mov_b32_e32 v25, v42
	v_pk_mov_b32 v[22:23], v[40:41], v[44:45] op_sel:[1,0]
	v_pk_add_f32 v[20:21], v[24:25], v[20:21]
	v_pk_add_f32 v[18:19], v[30:31], v[32:33]
	v_mov_b32_e32 v29, v45
	v_pk_add_f32 v[20:21], v[20:21], v[22:23]
	v_pk_add_f32 v[18:19], v[18:19], v[34:35]
	v_pk_add_f32 v[20:21], v[20:21], v[28:29]
	v_pk_add_f32 v[18:19], v[18:19], v[36:37]
	v_add_f32_e32 v0, v20, v21
	v_add_f32_e32 v0, v0, v18
	v_add_f32_e32 v0, v0, v19
	s_nop 1
	v_add_f32_dpp v0, v0, v0 quad_perm:[1,0,3,2] row_mask:0xf bank_mask:0xf bound_ctrl:1
	s_nop 1
	v_add_f32_dpp v0, v0, v0 quad_perm:[2,3,0,1] row_mask:0xf bank_mask:0xf bound_ctrl:1
	s_nop 1
	v_add_f32_dpp v0, v0, v0 row_half_mirror row_mask:0xf bank_mask:0xf bound_ctrl:1
	s_nop 1
	v_add_f32_dpp v0, v0, v0 row_mirror row_mask:0xf bank_mask:0xf bound_ctrl:1
	s_nop 1
	v_readlane_b32 vcc_lo, v0, 0
	v_readlane_b32 vcc_hi, v0, 16
	v_readlane_b32 s8, v0, 32
	v_readlane_b32 s9, v0, 48
	s_nop 1
	v_mov_b32_e32 v0, vcc_lo
	v_add_f32_e32 v0, vcc_hi, v0
	v_add_f32_e32 v0, s8, v0
	v_add_f32_e32 v0, s9, v0
	v_mov_b32_e32 v28, v30
	v_mov_b32_e32 v29, v32
	v_mov_b32_e32 v32, v31
	v_mov_b32_e32 v46, v34
	v_mov_b32_e32 v47, v36
	v_mov_b32_e32 v36, v35
	v_mul_f32_e32 v0, 0x3a800000, v0
	v_pk_add_f32 v[30:31], v[38:39], v[0:1] op_sel_hi:[1,0] neg_lo:[0,1] neg_hi:[0,1]
	v_pk_add_f32 v[34:35], v[40:41], v[0:1] op_sel_hi:[1,0] neg_lo:[0,1] neg_hi:[0,1]
	v_pk_add_f32 v[40:41], v[44:45], v[0:1] op_sel_hi:[1,0] neg_lo:[0,1] neg_hi:[0,1]
	v_pk_mul_f32 v[44:45], v[30:31], v[30:31]
	v_pk_add_f32 v[38:39], v[42:43], v[0:1] op_sel_hi:[1,0] neg_lo:[0,1] neg_hi:[0,1]
	v_pk_add_f32 v[28:29], v[28:29], v[0:1] op_sel_hi:[1,0] neg_lo:[0,1] neg_hi:[0,1]
	v_pk_add_f32 v[42:43], v[46:47], v[0:1] op_sel_hi:[1,0] neg_lo:[0,1] neg_hi:[0,1]
	v_pk_add_f32 v[32:33], v[32:33], v[0:1] op_sel_hi:[1,0] neg_lo:[0,1] neg_hi:[0,1]
	v_pk_add_f32 v[36:37], v[36:37], v[0:1] op_sel_hi:[1,0] neg_lo:[0,1] neg_hi:[0,1]
	v_pk_mul_f32 v[46:47], v[34:35], v[34:35]
	v_add_f32_e32 v0, v44, v45
	v_add_f32_e32 v0, v46, v0
	v_pk_mul_f32 v[48:49], v[38:39], v[38:39]
	v_add_f32_e32 v0, v47, v0
	v_add_f32_e32 v0, v48, v0
	v_pk_mul_f32 v[50:51], v[40:41], v[40:41]
	v_add_f32_e32 v0, v49, v0
	v_add_f32_e32 v0, v50, v0
	v_pk_mul_f32 v[52:53], v[28:29], v[28:29]
	v_add_f32_e32 v0, v51, v0
	v_add_f32_e32 v0, v52, v0
	v_pk_mul_f32 v[54:55], v[42:43], v[42:43]
	v_add_f32_e32 v0, v53, v0
	v_add_f32_e32 v0, v54, v0
	v_pk_mul_f32 v[56:57], v[32:33], v[32:33]
	v_add_f32_e32 v0, v55, v0
	v_add_f32_e32 v0, v56, v0
	v_pk_mul_f32 v[58:59], v[36:37], v[36:37]
	v_add_f32_e32 v0, v57, v0
	v_add_f32_e32 v0, v58, v0
	v_add_f32_e32 v0, v59, v0
	s_nop 1
	v_add_f32_dpp v0, v0, v0 quad_perm:[1,0,3,2] row_mask:0xf bank_mask:0xf bound_ctrl:1
	s_nop 1
	v_add_f32_dpp v0, v0, v0 quad_perm:[2,3,0,1] row_mask:0xf bank_mask:0xf bound_ctrl:1
	s_nop 1
	v_add_f32_dpp v0, v0, v0 row_half_mirror row_mask:0xf bank_mask:0xf bound_ctrl:1
	s_nop 1
	v_add_f32_dpp v0, v0, v0 row_mirror row_mask:0xf bank_mask:0xf bound_ctrl:1
	s_nop 1
	v_readlane_b32 vcc_lo, v0, 0
	v_readlane_b32 vcc_hi, v0, 16
	v_readlane_b32 s8, v0, 32
	v_readlane_b32 s9, v0, 48
	s_nop 1
	v_mov_b32_e32 v0, vcc_lo
	v_add_f32_e32 v0, vcc_hi, v0
	v_add_f32_e32 v0, s8, v0
	v_add_f32_e32 v0, s9, v0
	v_fmamk_f32 v0, v0, 0x3a800000, v224
	v_mul_f32_e32 v3, 0x4b800000, v0
	v_cmp_gt_f32_e32 vcc, s2, v0
	s_nop 1
	v_cndmask_b32_e32 v0, v0, v3, vcc
	v_rsq_f32_e32 v0, v0
	s_nop 0
	v_mul_f32_e32 v3, 0x45800000, v0
	v_cndmask_b32_e32 v0, v0, v3, vcc
	v_pk_mul_f32 v[30:31], v[30:31], v[0:1] op_sel_hi:[1,0]
	v_pk_mul_f32 v[34:35], v[34:35], v[0:1] op_sel_hi:[1,0]
	v_pk_fma_f32 v[18:19], v[60:61], v[30:31], v[76:77]
	v_pk_fma_f32 v[20:21], v[62:63], v[34:35], v[78:79]
	v_cvt_pk_f16_f32 v18, v18, v19
	v_cvt_pk_f16_f32 v19, v20, v21
	global_store_dwordx2 v[26:27], v[18:19], off
	v_pk_mul_f32 v[30:31], v[38:39], v[0:1] op_sel_hi:[1,0]
	v_pk_mul_f32 v[34:35], v[40:41], v[0:1] op_sel_hi:[1,0]
	v_pk_mul_f32 v[28:29], v[28:29], v[0:1] op_sel_hi:[1,0]
	v_cmp_lt_i32_e32 vcc, s3, v2
	s_or_b64 s[4:5], vcc, s[4:5]
	v_pk_fma_f32 v[18:19], v[64:65], v[30:31], v[80:81]
	v_pk_fma_f32 v[20:21], v[66:67], v[34:35], v[82:83]
	v_cvt_pk_f16_f32 v18, v18, v19
	v_cvt_pk_f16_f32 v19, v20, v21
	global_store_dwordx2 v[26:27], v[18:19], off offset:512
	v_pk_mul_f32 v[30:31], v[42:43], v[0:1] op_sel_hi:[1,0]
	v_pk_fma_f32 v[18:19], v[68:69], v[28:29], v[84:85]
	v_pk_fma_f32 v[20:21], v[70:71], v[30:31], v[86:87]
	v_cvt_pk_f16_f32 v18, v18, v19
	v_cvt_pk_f16_f32 v19, v20, v21
	global_store_dwordx2 v[26:27], v[18:19], off offset:1024
	v_pk_mul_f32 v[28:29], v[32:33], v[0:1] op_sel_hi:[1,0]
	v_pk_mul_f32 v[30:31], v[36:37], v[0:1] op_sel_hi:[1,0]
	v_pk_fma_f32 v[18:19], v[72:73], v[28:29], v[88:89]
	v_pk_fma_f32 v[20:21], v[74:75], v[30:31], v[90:91]
	v_cvt_pk_f16_f32 v18, v18, v19
	v_cvt_pk_f16_f32 v19, v20, v21
	global_store_dwordx2 v[26:27], v[18:19], off offset:1536
	s_andn2_b64 exec, exec, s[4:5]
	s_cbranch_execz .Lln2x_LBB0_1193
; __device__ __forceinline__ int bidx() { int t = blockIdx.x; asm volatile("" : "+s"(t)); return t; }
; __device__ __forceinline__ void ln_phase(const h16* V, float* X, h16* Xh, const float* g, const float* b, bool final_out, bool dry = false) {
;     ...
;   for (int row = bidx() * 4 + wid; row < T_; row += gridDim.x * 4) {
;     const h16* vr = V + (size_t)row * 1024;
;     f4 v[4];
;     float s = 0.f;
; #pragma unroll
;     for (int i = 0; i < 4; ++i) {
;       h4 hv = *(const h4*)(vr + i * 256 + lane * 4);
;       v[i][0] = (float)hv[0]; v[i][1] = (float)hv[1]; v[i][2] = (float)hv[2]; v[i][3] = (float)hv[3];
;       s += v[i][0] + v[i][1] + v[i][2] + v[i][3];
;     }
;     for (int o = 32; o > 0; o >>= 1) s += __shfl_xor(s, o);
;     const float mu = s * (1.f / 1024.f);
;     float q = 0.f;
; #pragma unroll
;     for (int i = 0; i < 4; ++i)
; #pragma unroll
;       for (int j = 0; j < 4; ++j) { float d = v[i][j] - mu; q += d * d; }
;     for (int o = 32; o > 0; o >>= 1) q += __shfl_xor(q, o);
;     const float rs = rsqrtf(q * (1.f / 1024.f) + 1e-5f);
;     if (dry && rs != 12345.678f) continue;
; #pragma unroll
;     for (int i = 0; i < 4; ++i) {
;       int c = i * 256 + lane * 4;
;       f4 gg = *(const f4*)(g + c), bb = *(const f4*)(b + c), o;
;       h4 oh;
; #pragma unroll
;       for (int j = 0; j < 4; ++j) { o[j] = (v[i][j] - mu) * rs * gg[j] + bb[j]; oh[j] = (h16)o[j]; }
;       if (final_out) *(f4*)(X + (size_t)row * 1024 + c) = o;
;       else *(h4*)(Xh + (size_t)row * 1024 + c) = oh;
;     }
	v_mov_b32_e32 v28, v1
	v_lshl_add_u64 v[26:27], v[10:11], 0, v[110:111]
	v_add_u32_e32 v2, s77, v2
	s_waitcnt vmcnt(7)
	v_cvt_f32_f16_e32 v31, v104
	s_waitcnt vmcnt(6)
	v_cvt_f32_f16_e32 v30, v106
	s_waitcnt vmcnt(5)
	v_cvt_f32_f16_sdwa v39, v108 dst_sel:DWORD dst_unused:UNUSED_PAD src0_sel:WORD_1
	v_cvt_f32_f16_e32 v38, v108
	v_cvt_f32_f16_e32 v40, v109
	s_waitcnt vmcnt(4)
	v_cvt_f32_f16_e32 v42, v102
	v_cvt_f32_f16_sdwa v43, v102 dst_sel:DWORD dst_unused:UNUSED_PAD src0_sel:WORD_1
	v_cvt_f32_f16_sdwa v41, v109 dst_sel:DWORD dst_unused:UNUSED_PAD src0_sel:WORD_1
	v_cvt_f32_f16_e32 v44, v103
	v_cvt_f32_f16_sdwa v45, v103 dst_sel:DWORD dst_unused:UNUSED_PAD src0_sel:WORD_1
	v_cvt_f32_f16_sdwa v33, v104 dst_sel:DWORD dst_unused:UNUSED_PAD src0_sel:WORD_1
	v_cvt_f32_f16_sdwa v32, v106 dst_sel:DWORD dst_unused:UNUSED_PAD src0_sel:WORD_1
	v_mov_b32_e32 v0, v39
	v_cvt_f32_f16_e32 v35, v105
	v_cvt_f32_f16_e32 v34, v107
	v_pk_add_f32 v[24:25], v[0:1], v[38:39]
	v_cvt_f32_f16_sdwa v37, v105 dst_sel:DWORD dst_unused:UNUSED_PAD src0_sel:WORD_1
	v_cvt_f32_f16_sdwa v36, v107 dst_sel:DWORD dst_unused:UNUSED_PAD src0_sel:WORD_1
	v_mov_b32_e32 v20, v40
	v_mov_b32_e32 v21, v43
	v_mov_b32_e32 v25, v42
	v_pk_mov_b32 v[22:23], v[40:41], v[44:45] op_sel:[1,0]
	v_pk_add_f32 v[20:21], v[24:25], v[20:21]
	v_pk_add_f32 v[18:19], v[30:31], v[32:33]
	v_mov_b32_e32 v29, v45
	v_pk_add_f32 v[20:21], v[20:21], v[22:23]
	v_pk_add_f32 v[18:19], v[18:19], v[34:35]
	v_pk_add_f32 v[20:21], v[20:21], v[28:29]
	v_pk_add_f32 v[18:19], v[18:19], v[36:37]
	v_add_f32_e32 v0, v20, v21
	v_add_f32_e32 v0, v0, v18
	v_add_f32_e32 v0, v0, v19
	s_nop 1
	v_add_f32_dpp v0, v0, v0 quad_perm:[1,0,3,2] row_mask:0xf bank_mask:0xf bound_ctrl:1
	s_nop 1
	v_add_f32_dpp v0, v0, v0 quad_perm:[2,3,0,1] row_mask:0xf bank_mask:0xf bound_ctrl:1
	s_nop 1
	v_add_f32_dpp v0, v0, v0 row_half_mirror row_mask:0xf bank_mask:0xf bound_ctrl:1
	s_nop 1
	v_add_f32_dpp v0, v0, v0 row_mirror row_mask:0xf bank_mask:0xf bound_ctrl:1
	s_nop 1
	v_readlane_b32 vcc_lo, v0, 0
	v_readlane_b32 vcc_hi, v0, 16
	v_readlane_b32 s8, v0, 32
	v_readlane_b32 s9, v0, 48
	s_nop 1
	v_mov_b32_e32 v0, vcc_lo
	v_add_f32_e32 v0, vcc_hi, v0
	v_add_f32_e32 v0, s8, v0
	v_add_f32_e32 v0, s9, v0
	v_mov_b32_e32 v28, v30
	v_mov_b32_e32 v29, v32
	v_mov_b32_e32 v32, v31
	v_mov_b32_e32 v46, v34
	v_mov_b32_e32 v47, v36
	v_mov_b32_e32 v36, v35
	v_mul_f32_e32 v0, 0x3a800000, v0
	v_pk_add_f32 v[30:31], v[38:39], v[0:1] op_sel_hi:[1,0] neg_lo:[0,1] neg_hi:[0,1]
	v_pk_add_f32 v[34:35], v[40:41], v[0:1] op_sel_hi:[1,0] neg_lo:[0,1] neg_hi:[0,1]
	v_pk_add_f32 v[40:41], v[44:45], v[0:1] op_sel_hi:[1,0] neg_lo:[0,1] neg_hi:[0,1]
	v_pk_mul_f32 v[44:45], v[30:31], v[30:31]
	v_pk_add_f32 v[38:39], v[42:43], v[0:1] op_sel_hi:[1,0] neg_lo:[0,1] neg_hi:[0,1]
	v_pk_add_f32 v[28:29], v[28:29], v[0:1] op_sel_hi:[1,0] neg_lo:[0,1] neg_hi:[0,1]
	v_pk_add_f32 v[42:43], v[46:47], v[0:1] op_sel_hi:[1,0] neg_lo:[0,1] neg_hi:[0,1]
	v_pk_add_f32 v[32:33], v[32:33], v[0:1] op_sel_hi:[1,0] neg_lo:[0,1] neg_hi:[0,1]
	v_pk_add_f32 v[36:37], v[36:37], v[0:1] op_sel_hi:[1,0] neg_lo:[0,1] neg_hi:[0,1]
	v_pk_mul_f32 v[46:47], v[34:35], v[34:35]
	v_add_f32_e32 v0, v44, v45
	v_add_f32_e32 v0, v46, v0
	v_pk_mul_f32 v[48:49], v[38:39], v[38:39]
	v_add_f32_e32 v0, v47, v0
	v_add_f32_e32 v0, v48, v0
	v_pk_mul_f32 v[50:51], v[40:41], v[40:41]
	v_add_f32_e32 v0, v49, v0
	v_add_f32_e32 v0, v50, v0
	v_pk_mul_f32 v[52:53], v[28:29], v[28:29]
	v_add_f32_e32 v0, v51, v0
	v_add_f32_e32 v0, v52, v0
	v_pk_mul_f32 v[54:55], v[42:43], v[42:43]
	v_add_f32_e32 v0, v53, v0
	v_add_f32_e32 v0, v54, v0
	v_pk_mul_f32 v[56:57], v[32:33], v[32:33]
	v_add_f32_e32 v0, v55, v0
	v_add_f32_e32 v0, v56, v0
	v_pk_mul_f32 v[58:59], v[36:37], v[36:37]
	v_add_f32_e32 v0, v57, v0
	v_add_f32_e32 v0, v58, v0
	v_add_f32_e32 v0, v59, v0
	s_nop 1
	v_add_f32_dpp v0, v0, v0 quad_perm:[1,0,3,2] row_mask:0xf bank_mask:0xf bound_ctrl:1
	s_nop 1
	v_add_f32_dpp v0, v0, v0 quad_perm:[2,3,0,1] row_mask:0xf bank_mask:0xf bound_ctrl:1
	s_nop 1
	v_add_f32_dpp v0, v0, v0 row_half_mirror row_mask:0xf bank_mask:0xf bound_ctrl:1
	s_nop 1
	v_add_f32_dpp v0, v0, v0 row_mirror row_mask:0xf bank_mask:0xf bound_ctrl:1
	s_nop 1
	v_readlane_b32 vcc_lo, v0, 0
	v_readlane_b32 vcc_hi, v0, 16
	v_readlane_b32 s8, v0, 32
	v_readlane_b32 s9, v0, 48
	s_nop 1
	v_mov_b32_e32 v0, vcc_lo
	v_add_f32_e32 v0, vcc_hi, v0
	v_add_f32_e32 v0, s8, v0
	v_add_f32_e32 v0, s9, v0
	v_fmamk_f32 v0, v0, 0x3a800000, v224
	v_mul_f32_e32 v3, 0x4b800000, v0
	v_cmp_gt_f32_e32 vcc, s2, v0
	s_nop 1
	v_cndmask_b32_e32 v0, v0, v3, vcc
	v_rsq_f32_e32 v0, v0
	s_nop 0
	v_mul_f32_e32 v3, 0x45800000, v0
	v_cndmask_b32_e32 v0, v0, v3, vcc
	v_pk_mul_f32 v[30:31], v[30:31], v[0:1] op_sel_hi:[1,0]
	v_pk_mul_f32 v[34:35], v[34:35], v[0:1] op_sel_hi:[1,0]
	v_pk_fma_f32 v[18:19], v[60:61], v[30:31], v[76:77]
	v_pk_fma_f32 v[20:21], v[62:63], v[34:35], v[78:79]
	v_cvt_pk_f16_f32 v18, v18, v19
	v_cvt_pk_f16_f32 v19, v20, v21
	global_store_dwordx2 v[26:27], v[18:19], off
	v_pk_mul_f32 v[30:31], v[38:39], v[0:1] op_sel_hi:[1,0]
	v_pk_mul_f32 v[34:35], v[40:41], v[0:1] op_sel_hi:[1,0]
	v_pk_mul_f32 v[28:29], v[28:29], v[0:1] op_sel_hi:[1,0]
	v_cmp_lt_i32_e32 vcc, s3, v2
	s_or_b64 s[4:5], vcc, s[4:5]
	v_pk_fma_f32 v[18:19], v[64:65], v[30:31], v[80:81]
	v_pk_fma_f32 v[20:21], v[66:67], v[34:35], v[82:83]
	v_cvt_pk_f16_f32 v18, v18, v19
	v_cvt_pk_f16_f32 v19, v20, v21
	global_store_dwordx2 v[26:27], v[18:19], off offset:512
	v_pk_mul_f32 v[30:31], v[42:43], v[0:1] op_sel_hi:[1,0]
	v_pk_fma_f32 v[18:19], v[68:69], v[28:29], v[84:85]
	v_pk_fma_f32 v[20:21], v[70:71], v[30:31], v[86:87]
	v_cvt_pk_f16_f32 v18, v18, v19
	v_cvt_pk_f16_f32 v19, v20, v21
	global_store_dwordx2 v[26:27], v[18:19], off offset:1024
	v_pk_mul_f32 v[28:29], v[32:33], v[0:1] op_sel_hi:[1,0]
	v_pk_mul_f32 v[30:31], v[36:37], v[0:1] op_sel_hi:[1,0]
	v_pk_fma_f32 v[18:19], v[72:73], v[28:29], v[88:89]
	v_pk_fma_f32 v[20:21], v[74:75], v[30:31], v[90:91]
	v_cvt_pk_f16_f32 v18, v18, v19
	v_cvt_pk_f16_f32 v19, v20, v21
	global_store_dwordx2 v[26:27], v[18:19], off offset:1536
	s_andn2_b64 exec, exec, s[4:5]
	s_cbranch_execnz .LBB0_1193
.Lln2x_LBB0_1193:
.LBB0_1194:
	s_or_b64 exec, exec, s[0:1]
	v_lshlrev_b32_e32 v18, 4, v180
	ds_read_b128 v[60:63], v18
	ds_read_b128 v[64:67], v18 offset:4096
	ds_read_b128 v[68:71], v18 offset:8192
	ds_read_b128 v[72:75], v18 offset:12288
	ds_read_b128 v[76:79], v18 offset:16384
	ds_read_b128 v[80:83], v18 offset:20480
	ds_read_b128 v[84:87], v18 offset:24576
	ds_read_b128 v[88:91], v18 offset:28672
	s_waitcnt lgkmcnt(0)
	s_waitcnt vmcnt(0)
	s_barrier
	s_and_saveexec_b64 s[0:1], s[48:49]
	s_cbranch_execz .LBB0_1231
	s_mov_b64 s[4:5], exec
	v_mbcnt_lo_u32_b32 v0, s4, 0
	v_mbcnt_hi_u32_b32 v0, s5, v0
	v_cmp_eq_u32_e32 vcc, 0, v0
	s_waitcnt vmcnt(0) expcnt(0) lgkmcnt(0)
	s_and_saveexec_b64 s[6:7], vcc
	s_cbranch_execz .LBB0_1197
	s_bcnt1_i32_b64 s2, s[4:5]
	v_mov_b32_e32 v2, s2
	v_readlane_b32 s2, v247, 8
	v_readlane_b32 s3, v247, 9
	s_nop 4
	global_atomic_add v2, v1, v2, s[2:3] sc0

; __device__ __forceinline__ int bidx() { int t = blockIdx.x; asm volatile("" : "+s"(t)); return t; }
; __device__ __forceinline__ void ln_phase(const h16* V, float* X, h16* Xh, const float* g, const float* b, bool final_out, bool dry = false) {
;     ...
;   for (int row = bidx() * 4 + wid; row < T_; row += gridDim.x * 4) {
;     const h16* vr = V + (size_t)row * 1024;
;     f4 v[4];
;     float s = 0.f;
; #pragma unroll
;     for (int i = 0; i < 4; ++i) {
;       h4 hv = *(const h4*)(vr + i * 256 + lane * 4);
;       v[i][0] = (float)hv[0]; v[i][1] = (float)hv[1]; v[i][2] = (float)hv[2]; v[i][3] = (float)hv[3];
;       s += v[i][0] + v[i][1] + v[i][2] + v[i][3];
;     }
;     for (int o = 32; o > 0; o >>= 1) s += __shfl_xor(s, o);
;     const float mu = s * (1.f / 1024.f);
;     float q = 0.f;
; #pragma unroll
;     for (int i = 0; i < 4; ++i)
; #pragma unroll
;       for (int j = 0; j < 4; ++j) { float d = v[i][j] - mu; q += d * d; }
;     for (int o = 32; o > 0; o >>= 1) q += __shfl_xor(q, o);
;     const float rs = rsqrtf(q * (1.f / 1024.f) + 1e-5f);
;     if (dry && rs != 12345.678f) continue;
; #pragma unroll
;     for (int i = 0; i < 4; ++i) {
;       int c = i * 256 + lane * 4;
;       f4 gg = *(const f4*)(g + c), bb = *(const f4*)(b + c), o;
;       h4 oh;
; #pragma unroll
;       for (int j = 0; j < 4; ++j) { o[j] = (v[i][j] - mu) * rs * gg[j] + bb[j]; oh[j] = (h16)o[j]; }
;       if (final_out) *(f4*)(X + (size_t)row * 1024 + c) = o;
;       else *(h4*)(Xh + (size_t)row * 1024 + c) = oh;
;     }
.LBB0_1371:
	v_ashrrev_i32_e32 v3, 31, v2
	v_lshlrev_b64 v[26:27], 11, v[2:3]
	v_lshl_add_u64 v[18:19], v[4:5], 0, v[26:27]
	global_load_dwordx2 v[20:21], v[18:19], off offset:1536
	global_load_dwordx2 v[22:23], v[18:19], off offset:1024
	global_load_dwordx2 v[24:25], v[18:19], off
	s_nop 0
	global_load_dwordx2 v[18:19], v[18:19], off offset:512
	v_add_u32_e32 v110, s77, v2
	v_ashrrev_i32_e32 v111, 31, v110
	v_lshlrev_b64 v[110:111], 11, v[110:111]
	v_lshl_add_u64 v[102:103], v[4:5], 0, v[110:111]
	global_load_dwordx2 v[104:105], v[102:103], off offset:1536
	global_load_dwordx2 v[106:107], v[102:103], off offset:1024
	global_load_dwordx2 v[108:109], v[102:103], off
	s_nop 0
	global_load_dwordx2 v[102:103], v[102:103], off offset:512
	v_mov_b32_e32 v28, v1
	v_lshl_add_u64 v[26:27], v[10:11], 0, v[26:27]
	v_add_u32_e32 v2, s77, v2
	s_waitcnt vmcnt(7)
	v_cvt_f32_f16_e32 v31, v20
	s_waitcnt vmcnt(6)
	v_cvt_f32_f16_e32 v30, v22
	s_waitcnt vmcnt(5)
	v_cvt_f32_f16_sdwa v39, v24 dst_sel:DWORD dst_unused:UNUSED_PAD src0_sel:WORD_1
	v_cvt_f32_f16_e32 v38, v24
	v_cvt_f32_f16_e32 v40, v25
	s_waitcnt vmcnt(4)
	v_cvt_f32_f16_e32 v42, v18
	v_cvt_f32_f16_sdwa v43, v18 dst_sel:DWORD dst_unused:UNUSED_PAD src0_sel:WORD_1
	v_cvt_f32_f16_sdwa v41, v25 dst_sel:DWORD dst_unused:UNUSED_PAD src0_sel:WORD_1
	v_cvt_f32_f16_e32 v44, v19
	v_cvt_f32_f16_sdwa v45, v19 dst_sel:DWORD dst_unused:UNUSED_PAD src0_sel:WORD_1
	v_cvt_f32_f16_sdwa v33, v20 dst_sel:DWORD dst_unused:UNUSED_PAD src0_sel:WORD_1
	v_cvt_f32_f16_sdwa v32, v22 dst_sel:DWORD dst_unused:UNUSED_PAD src0_sel:WORD_1
	v_mov_b32_e32 v0, v39
	v_cvt_f32_f16_e32 v35, v21
	v_cvt_f32_f16_e32 v34, v23
	v_pk_add_f32 v[24:25], v[0:1], v[38:39]
	v_cvt_f32_f16_sdwa v37, v21 dst_sel:DWORD dst_unused:UNUSED_PAD src0_sel:WORD_1
	v_cvt_f32_f16_sdwa v36, v23 dst_sel:DWORD dst_unused:UNUSED_PAD src0_sel:WORD_1
	v_mov_b32_e32 v20, v40
	v_mov_b32_e32 v21, v43
	v_mov_b32_e32 v25, v42
	v_pk_mov_b32 v[22:23], v[40:41], v[44:45] op_sel:[1,0]
	v_pk_add_f32 v[20:21], v[24:25], v[20:21]
	v_pk_add_f32 v[18:19], v[30:31], v[32:33]
	v_mov_b32_e32 v29, v45
	v_pk_add_f32 v[20:21], v[20:21], v[22:23]
	v_pk_add_f32 v[18:19], v[18:19], v[34:35]
	v_pk_add_f32 v[20:21], v[20:21], v[28:29]
	v_pk_add_f32 v[18:19], v[18:19], v[36:37]
	v_add_f32_e32 v0, v20, v21
	v_add_f32_e32 v0, v0, v18
	v_add_f32_e32 v0, v0, v19
	s_nop 1
	v_add_f32_dpp v0, v0, v0 quad_perm:[1,0,3,2] row_mask:0xf bank_mask:0xf bound_ctrl:1
	s_nop 1
	v_add_f32_dpp v0, v0, v0 quad_perm:[2,3,0,1] row_mask:0xf bank_mask:0xf bound_ctrl:1
	s_nop 1
	v_add_f32_dpp v0, v0, v0 row_half_mirror row_mask:0xf bank_mask:0xf bound_ctrl:1
	s_nop 1
	v_add_f32_dpp v0, v0, v0 row_mirror row_mask:0xf bank_mask:0xf bound_ctrl:1
	s_nop 1
	v_readlane_b32 vcc_lo, v0, 0
	v_readlane_b32 vcc_hi, v0, 16
	v_readlane_b32 s8, v0, 32
	v_readlane_b32 s9, v0, 48
	s_nop 1
	v_mov_b32_e32 v0, vcc_lo
	v_add_f32_e32 v0, vcc_hi, v0
	v_add_f32_e32 v0, s8, v0
	v_add_f32_e32 v0, s9, v0
	v_mov_b32_e32 v28, v30
	v_mov_b32_e32 v29, v32
	v_mov_b32_e32 v32, v31
	v_mov_b32_e32 v46, v34
	v_mov_b32_e32 v47, v36
	v_mov_b32_e32 v36, v35
	v_mul_f32_e32 v0, 0x3a800000, v0
	v_pk_add_f32 v[30:31], v[38:39], v[0:1] op_sel_hi:[1,0] neg_lo:[0,1] neg_hi:[0,1]
	v_pk_add_f32 v[34:35], v[40:41], v[0:1] op_sel_hi:[1,0] neg_lo:[0,1] neg_hi:[0,1]
	v_pk_add_f32 v[40:41], v[44:45], v[0:1] op_sel_hi:[1,0] neg_lo:[0,1] neg_hi:[0,1]
	v_pk_mul_f32 v[44:45], v[30:31], v[30:31]
	v_pk_add_f32 v[38:39], v[42:43], v[0:1] op_sel_hi:[1,0] neg_lo:[0,1] neg_hi:[0,1]
	v_pk_add_f32 v[28:29], v[28:29], v[0:1] op_sel_hi:[1,0] neg_lo:[0,1] neg_hi:[0,1]
	v_pk_add_f32 v[42:43], v[46:47], v[0:1] op_sel_hi:[1,0] neg_lo:[0,1] neg_hi:[0,1]
	v_pk_add_f32 v[32:33], v[32:33], v[0:1] op_sel_hi:[1,0] neg_lo:[0,1] neg_hi:[0,1]
	v_pk_add_f32 v[36:37], v[36:37], v[0:1] op_sel_hi:[1,0] neg_lo:[0,1] neg_hi:[0,1]
	v_pk_mul_f32 v[46:47], v[34:35], v[34:35]
	v_add_f32_e32 v0, v44, v45
	v_add_f32_e32 v0, v46, v0
	v_pk_mul_f32 v[48:49], v[38:39], v[38:39]
	v_add_f32_e32 v0, v47, v0
	v_add_f32_e32 v0, v48, v0
	v_pk_mul_f32 v[50:51], v[40:41], v[40:41]
	v_add_f32_e32 v0, v49, v0
	v_add_f32_e32 v0, v50, v0
	v_pk_mul_f32 v[52:53], v[28:29], v[28:29]
	v_add_f32_e32 v0, v51, v0
	v_add_f32_e32 v0, v52, v0
	v_pk_mul_f32 v[54:55], v[42:43], v[42:43]
	v_add_f32_e32 v0, v53, v0
	v_add_f32_e32 v0, v54, v0
	v_pk_mul_f32 v[56:57], v[32:33], v[32:33]
	v_add_f32_e32 v0, v55, v0
	v_add_f32_e32 v0, v56, v0
	v_pk_mul_f32 v[58:59], v[36:37], v[36:37]
	v_add_f32_e32 v0, v57, v0
	v_add_f32_e32 v0, v58, v0
	v_add_f32_e32 v0, v59, v0
	s_nop 1
	v_add_f32_dpp v0, v0, v0 quad_perm:[1,0,3,2] row_mask:0xf bank_mask:0xf bound_ctrl:1
	s_nop 1
	v_add_f32_dpp v0, v0, v0 quad_perm:[2,3,0,1] row_mask:0xf bank_mask:0xf bound_ctrl:1
	s_nop 1
	v_add_f32_dpp v0, v0, v0 row_half_mirror row_mask:0xf bank_mask:0xf bound_ctrl:1
	s_nop 1
	v_add_f32_dpp v0, v0, v0 row_mirror row_mask:0xf bank_mask:0xf bound_ctrl:1
	s_nop 1
	v_readlane_b32 vcc_lo, v0, 0
	v_readlane_b32 vcc_hi, v0, 16
	v_readlane_b32 s8, v0, 32
	v_readlane_b32 s9, v0, 48
	s_nop 1
	v_mov_b32_e32 v0, vcc_lo
	v_add_f32_e32 v0, vcc_hi, v0
	v_add_f32_e32 v0, s8, v0
	v_add_f32_e32 v0, s9, v0
	v_fmamk_f32 v0, v0, 0x3a800000, v224
	v_mul_f32_e32 v3, 0x4b800000, v0
	v_cmp_gt_f32_e32 vcc, s2, v0
	s_nop 1
	v_cndmask_b32_e32 v0, v0, v3, vcc
	v_rsq_f32_e32 v0, v0
	s_nop 0
	v_mul_f32_e32 v3, 0x45800000, v0
	v_cndmask_b32_e32 v0, v0, v3, vcc
	v_pk_mul_f32 v[30:31], v[30:31], v[0:1] op_sel_hi:[1,0]
	v_pk_mul_f32 v[34:35], v[34:35], v[0:1] op_sel_hi:[1,0]
	v_pk_fma_f32 v[18:19], v[60:61], v[30:31], v[76:77]
	v_pk_fma_f32 v[20:21], v[62:63], v[34:35], v[78:79]
	v_cvt_pk_f16_f32 v18, v18, v19
	v_cvt_pk_f16_f32 v19, v20, v21
	global_store_dwordx2 v[26:27], v[18:19], off
	v_pk_mul_f32 v[30:31], v[38:39], v[0:1] op_sel_hi:[1,0]
	v_pk_mul_f32 v[34:35], v[40:41], v[0:1] op_sel_hi:[1,0]
	v_pk_mul_f32 v[28:29], v[28:29], v[0:1] op_sel_hi:[1,0]
	v_cmp_lt_i32_e32 vcc, s17, v2
	s_or_b64 s[4:5], vcc, s[4:5]
	v_pk_fma_f32 v[18:19], v[64:65], v[30:31], v[80:81]
	v_pk_fma_f32 v[20:21], v[66:67], v[34:35], v[82:83]
	v_cvt_pk_f16_f32 v18, v18, v19
	v_cvt_pk_f16_f32 v19, v20, v21
	global_store_dwordx2 v[26:27], v[18:19], off offset:512
	v_pk_mul_f32 v[30:31], v[42:43], v[0:1] op_sel_hi:[1,0]
	v_pk_fma_f32 v[18:19], v[68:69], v[28:29], v[84:85]
	v_pk_fma_f32 v[20:21], v[70:71], v[30:31], v[86:87]
	v_cvt_pk_f16_f32 v18, v18, v19
	v_cvt_pk_f16_f32 v19, v20, v21
	global_store_dwordx2 v[26:27], v[18:19], off offset:1024
	v_pk_mul_f32 v[28:29], v[32:33], v[0:1] op_sel_hi:[1,0]
	v_pk_mul_f32 v[30:31], v[36:37], v[0:1] op_sel_hi:[1,0]
	v_pk_fma_f32 v[18:19], v[72:73], v[28:29], v[88:89]
	v_pk_fma_f32 v[20:21], v[74:75], v[30:31], v[90:91]
	v_cvt_pk_f16_f32 v18, v18, v19
	v_cvt_pk_f16_f32 v19, v20, v21
	global_store_dwordx2 v[26:27], v[18:19], off offset:1536
	s_andn2_b64 exec, exec, s[4:5]
	s_cbranch_execz .Lln2x_LBB0_1371
; __device__ __forceinline__ int bidx() { int t = blockIdx.x; asm volatile("" : "+s"(t)); return t; }
; __device__ __forceinline__ void ln_phase(const h16* V, float* X, h16* Xh, const float* g, const float* b, bool final_out, bool dry = false) {
;     ...
;   for (int row = bidx() * 4 + wid; row < T_; row += gridDim.x * 4) {
;     const h16* vr = V + (size_t)row * 1024;
;     f4 v[4];
;     float s = 0.f;
; #pragma unroll
;     for (int i = 0; i < 4; ++i) {
;       h4 hv = *(const h4*)(vr + i * 256 + lane * 4);
;       v[i][0] = (float)hv[0]; v[i][1] = (float)hv[1]; v[i][2] = (float)hv[2]; v[i][3] = (float)hv[3];
;       s += v[i][0] + v[i][1] + v[i][2] + v[i][3];
;     }
;     for (int o = 32; o > 0; o >>= 1) s += __shfl_xor(s, o);
;     const float mu = s * (1.f / 1024.f);
;     float q = 0.f;
; #pragma unroll
;     for (int i = 0; i < 4; ++i)
; #pragma unroll
;       for (int j = 0; j < 4; ++j) { float d = v[i][j] - mu; q += d * d; }
;     for (int o = 32; o > 0; o >>= 1) q += __shfl_xor(q, o);
;     const float rs = rsqrtf(q * (1.f / 1024.f) + 1e-5f);
;     if (dry && rs != 12345.678f) continue;
; #pragma unroll
;     for (int i = 0; i < 4; ++i) {
;       int c = i * 256 + lane * 4;
;       f4 gg = *(const f4*)(g + c), bb = *(const f4*)(b + c), o;
;       h4 oh;
; #pragma unroll
;       for (int j = 0; j < 4; ++j) { o[j] = (v[i][j] - mu) * rs * gg[j] + bb[j]; oh[j] = (h16)o[j]; }
;       if (final_out) *(f4*)(X + (size_t)row * 1024 + c) = o;
;       else *(h4*)(Xh + (size_t)row * 1024 + c) = oh;
;     }
	v_mov_b32_e32 v28, v1
	v_lshl_add_u64 v[26:27], v[10:11], 0, v[110:111]
	v_add_u32_e32 v2, s77, v2
	s_waitcnt vmcnt(7)
	v_cvt_f32_f16_e32 v31, v104
	s_waitcnt vmcnt(6)
	v_cvt_f32_f16_e32 v30, v106
	s_waitcnt vmcnt(5)
	v_cvt_f32_f16_sdwa v39, v108 dst_sel:DWORD dst_unused:UNUSED_PAD src0_sel:WORD_1
	v_cvt_f32_f16_e32 v38, v108
	v_cvt_f32_f16_e32 v40, v109
	s_waitcnt vmcnt(4)
	v_cvt_f32_f16_e32 v42, v102
	v_cvt_f32_f16_sdwa v43, v102 dst_sel:DWORD dst_unused:UNUSED_PAD src0_sel:WORD_1
	v_cvt_f32_f16_sdwa v41, v109 dst_sel:DWORD dst_unused:UNUSED_PAD src0_sel:WORD_1
	v_cvt_f32_f16_e32 v44, v103
	v_cvt_f32_f16_sdwa v45, v103 dst_sel:DWORD dst_unused:UNUSED_PAD src0_sel:WORD_1
	v_cvt_f32_f16_sdwa v33, v104 dst_sel:DWORD dst_unused:UNUSED_PAD src0_sel:WORD_1
	v_cvt_f32_f16_sdwa v32, v106 dst_sel:DWORD dst_unused:UNUSED_PAD src0_sel:WORD_1
	v_mov_b32_e32 v0, v39
	v_cvt_f32_f16_e32 v35, v105
	v_cvt_f32_f16_e32 v34, v107
	v_pk_add_f32 v[24:25], v[0:1], v[38:39]
	v_cvt_f32_f16_sdwa v37, v105 dst_sel:DWORD dst_unused:UNUSED_PAD src0_sel:WORD_1
	v_cvt_f32_f16_sdwa v36, v107 dst_sel:DWORD dst_unused:UNUSED_PAD src0_sel:WORD_1
	v_mov_b32_e32 v20, v40
	v_mov_b32_e32 v21, v43
	v_mov_b32_e32 v25, v42
	v_pk_mov_b32 v[22:23], v[40:41], v[44:45] op_sel:[1,0]
	v_pk_add_f32 v[20:21], v[24:25], v[20:21]
	v_pk_add_f32 v[18:19], v[30:31], v[32:33]
	v_mov_b32_e32 v29, v45
	v_pk_add_f32 v[20:21], v[20:21], v[22:23]
	v_pk_add_f32 v[18:19], v[18:19], v[34:35]
	v_pk_add_f32 v[20:21], v[20:21], v[28:29]
	v_pk_add_f32 v[18:19], v[18:19], v[36:37]
	v_add_f32_e32 v0, v20, v21
	v_add_f32_e32 v0, v0, v18
	v_add_f32_e32 v0, v0, v19
	s_nop 1
	v_add_f32_dpp v0, v0, v0 quad_perm:[1,0,3,2] row_mask:0xf bank_mask:0xf bound_ctrl:1
	s_nop 1
	v_add_f32_dpp v0, v0, v0 quad_perm:[2,3,0,1] row_mask:0xf bank_mask:0xf bound_ctrl:1
	s_nop 1
	v_add_f32_dpp v0, v0, v0 row_half_mirror row_mask:0xf bank_mask:0xf bound_ctrl:1
	s_nop 1
	v_add_f32_dpp v0, v0, v0 row_mirror row_mask:0xf bank_mask:0xf bound_ctrl:1
	s_nop 1
	v_readlane_b32 vcc_lo, v0, 0
	v_readlane_b32 vcc_hi, v0, 16
	v_readlane_b32 s8, v0, 32
	v_readlane_b32 s9, v0, 48
	s_nop 1
	v_mov_b32_e32 v0, vcc_lo
	v_add_f32_e32 v0, vcc_hi, v0
	v_add_f32_e32 v0, s8, v0
	v_add_f32_e32 v0, s9, v0
	v_mov_b32_e32 v28, v30
	v_mov_b32_e32 v29, v32
	v_mov_b32_e32 v32, v31
	v_mov_b32_e32 v46, v34
	v_mov_b32_e32 v47, v36
	v_mov_b32_e32 v36, v35
	v_mul_f32_e32 v0, 0x3a800000, v0
	v_pk_add_f32 v[30:31], v[38:39], v[0:1] op_sel_hi:[1,0] neg_lo:[0,1] neg_hi:[0,1]
	v_pk_add_f32 v[34:35], v[40:41], v[0:1] op_sel_hi:[1,0] neg_lo:[0,1] neg_hi:[0,1]
	v_pk_add_f32 v[40:41], v[44:45], v[0:1] op_sel_hi:[1,0] neg_lo:[0,1] neg_hi:[0,1]
	v_pk_mul_f32 v[44:45], v[30:31], v[30:31]
	v_pk_add_f32 v[38:39], v[42:43], v[0:1] op_sel_hi:[1,0] neg_lo:[0,1] neg_hi:[0,1]
	v_pk_add_f32 v[28:29], v[28:29], v[0:1] op_sel_hi:[1,0] neg_lo:[0,1] neg_hi:[0,1]
	v_pk_add_f32 v[42:43], v[46:47], v[0:1] op_sel_hi:[1,0] neg_lo:[0,1] neg_hi:[0,1]
	v_pk_add_f32 v[32:33], v[32:33], v[0:1] op_sel_hi:[1,0] neg_lo:[0,1] neg_hi:[0,1]
	v_pk_add_f32 v[36:37], v[36:37], v[0:1] op_sel_hi:[1,0] neg_lo:[0,1] neg_hi:[0,1]
	v_pk_mul_f32 v[46:47], v[34:35], v[34:35]
	v_add_f32_e32 v0, v44, v45
	v_add_f32_e32 v0, v46, v0
	v_pk_mul_f32 v[48:49], v[38:39], v[38:39]
	v_add_f32_e32 v0, v47, v0
	v_add_f32_e32 v0, v48, v0
	v_pk_mul_f32 v[50:51], v[40:41], v[40:41]
	v_add_f32_e32 v0, v49, v0
	v_add_f32_e32 v0, v50, v0
	v_pk_mul_f32 v[52:53], v[28:29], v[28:29]
	v_add_f32_e32 v0, v51, v0
	v_add_f32_e32 v0, v52, v0
	v_pk_mul_f32 v[54:55], v[42:43], v[42:43]
	v_add_f32_e32 v0, v53, v0
	v_add_f32_e32 v0, v54, v0
	v_pk_mul_f32 v[56:57], v[32:33], v[32:33]
	v_add_f32_e32 v0, v55, v0
	v_add_f32_e32 v0, v56, v0
	v_pk_mul_f32 v[58:59], v[36:37], v[36:37]
	v_add_f32_e32 v0, v57, v0
	v_add_f32_e32 v0, v58, v0
	v_add_f32_e32 v0, v59, v0
	s_nop 1
	v_add_f32_dpp v0, v0, v0 quad_perm:[1,0,3,2] row_mask:0xf bank_mask:0xf bound_ctrl:1
	s_nop 1
	v_add_f32_dpp v0, v0, v0 quad_perm:[2,3,0,1] row_mask:0xf bank_mask:0xf bound_ctrl:1
	s_nop 1
	v_add_f32_dpp v0, v0, v0 row_half_mirror row_mask:0xf bank_mask:0xf bound_ctrl:1
	s_nop 1
	v_add_f32_dpp v0, v0, v0 row_mirror row_mask:0xf bank_mask:0xf bound_ctrl:1
	s_nop 1
	v_readlane_b32 vcc_lo, v0, 0
	v_readlane_b32 vcc_hi, v0, 16
	v_readlane_b32 s8, v0, 32
	v_readlane_b32 s9, v0, 48
	s_nop 1
	v_mov_b32_e32 v0, vcc_lo
	v_add_f32_e32 v0, vcc_hi, v0
	v_add_f32_e32 v0, s8, v0
	v_add_f32_e32 v0, s9, v0
	v_fmamk_f32 v0, v0, 0x3a800000, v224
	v_mul_f32_e32 v3, 0x4b800000, v0
	v_cmp_gt_f32_e32 vcc, s2, v0
	s_nop 1
	v_cndmask_b32_e32 v0, v0, v3, vcc
	v_rsq_f32_e32 v0, v0
	s_nop 0
	v_mul_f32_e32 v3, 0x45800000, v0
	v_cndmask_b32_e32 v0, v0, v3, vcc
	v_pk_mul_f32 v[30:31], v[30:31], v[0:1] op_sel_hi:[1,0]
	v_pk_mul_f32 v[34:35], v[34:35], v[0:1] op_sel_hi:[1,0]
	v_pk_fma_f32 v[18:19], v[60:61], v[30:31], v[76:77]
	v_pk_fma_f32 v[20:21], v[62:63], v[34:35], v[78:79]
	v_cvt_pk_f16_f32 v18, v18, v19
	v_cvt_pk_f16_f32 v19, v20, v21
	global_store_dwordx2 v[26:27], v[18:19], off
	v_pk_mul_f32 v[30:31], v[38:39], v[0:1] op_sel_hi:[1,0]
	v_pk_mul_f32 v[34:35], v[40:41], v[0:1] op_sel_hi:[1,0]
	v_pk_mul_f32 v[28:29], v[28:29], v[0:1] op_sel_hi:[1,0]
	v_cmp_lt_i32_e32 vcc, s17, v2
	s_or_b64 s[4:5], vcc, s[4:5]
	v_pk_fma_f32 v[18:19], v[64:65], v[30:31], v[80:81]
	v_pk_fma_f32 v[20:21], v[66:67], v[34:35], v[82:83]
	v_cvt_pk_f16_f32 v18, v18, v19
	v_cvt_pk_f16_f32 v19, v20, v21
	global_store_dwordx2 v[26:27], v[18:19], off offset:512
	v_pk_mul_f32 v[30:31], v[42:43], v[0:1] op_sel_hi:[1,0]
	v_pk_fma_f32 v[18:19], v[68:69], v[28:29], v[84:85]
	v_pk_fma_f32 v[20:21], v[70:71], v[30:31], v[86:87]
	v_cvt_pk_f16_f32 v18, v18, v19
	v_cvt_pk_f16_f32 v19, v20, v21
	global_store_dwordx2 v[26:27], v[18:19], off offset:1024
	v_pk_mul_f32 v[28:29], v[32:33], v[0:1] op_sel_hi:[1,0]
	v_pk_mul_f32 v[30:31], v[36:37], v[0:1] op_sel_hi:[1,0]
	v_pk_fma_f32 v[18:19], v[72:73], v[28:29], v[88:89]
	v_pk_fma_f32 v[20:21], v[74:75], v[30:31], v[90:91]
	v_cvt_pk_f16_f32 v18, v18, v19
	v_cvt_pk_f16_f32 v19, v20, v21
	global_store_dwordx2 v[26:27], v[18:19], off offset:1536
	s_andn2_b64 exec, exec, s[4:5]
	s_cbranch_execnz .LBB0_1371
